# v24: v16 + GEMM phases: one static s_setprio 1 for waves 0-3 at phase entry, per-segment flips neutralised
# baseline (speedup 1.0000x reference)
; __device__ __forceinline__ int mk_tid() { return mk_wave() * 64 + mk_lane(); }
;     __host__ __device__ bool next(int i, Unit& u) const { return StaticOrder::next(i >> 1, u); }
; template <class Epi, class Sched, bool ALIGN_EPI = false, bool SP2 = false>
; __device__ __forceinline__ void gemm_phase(PG8_LAS unsigned char* lds, const Gemm g, const Sched& S, const Epi& E) {
;     int tid_ = mk_tid(); asm volatile("" : "+v"(tid_));
;     const int tid = tid_, wid = __builtin_amdgcn_readfirstlane(tid >> 6), lane = tid & 63, wr = wid >> 2, wc = wid & 3, fr = lane & 15, fq = lane >> 4;
;     const int K = g.K, nt = K / BK;
;     unsigned voffA[2], voffB[2];
; #pragma unroll
;     for (int i = 0; i < 2; ++i) { int R, C; stage_rc(tid * 16 + i * 8192, R, C); const int Rb = Epi::PERM ? ((R & ~31) + perm32(R & 31)) : R;
;         voffA[i] = (unsigned)(R * g.lda + C) * 2u; voffB[i] = (unsigned)(Rb * g.ldb + C) * 2u; }
;     const size_t kstep = (size_t)(BK * 2);
;     const size_t hsA = (size_t)HALF * g.lda * 2, hsB = (size_t)HALF * g.ldb * 2;
;     const size_t tsA = 2 * hsA, tsB = 2 * hsB;
;     const unsigned ldsbase = (unsigned)(unsigned long long)lds;
;     const unsigned ldsw = (unsigned)wid * 1024u;
;     const int aoff = lds_byte(wr * 64 + fr, fq * 8), boff = lds_byte(wc * 32 + fr, fq * 8);
;     ...
;     Unit cur, nxt; int ui = 0; bool epi_ran = false;
;     if (!S.next(0, cur)) return;
;     f32x4 acc[2][2][4][2];
; #pragma unroll
;     for (int a = 0; a < 2; ++a)
; #pragma unroll
;         for (int b = 0; b < 2; ++b)
; #pragma unroll
;             for (int m = 0; m < 4; ++m)
; #pragma unroll
;                 for (int n = 0; n < 2; ++n) acc[a][b][m][n] = (f32x4){0.f, 0.f, 0.f, 0.f};
;     bf16x8 At[4][2], B0[2][2], B1[2][2];
;     const char* cA = (const char*)g.A + (size_t)cur.pm * tsA + (size_t)cur.k0 * 2; const char* cB = (const char*)g.Bt + (size_t)cur.pn * tsB + (size_t)cur.k0 * 2;
;     S.a_ready(cur);
;     if constexpr (SP2) {
;         PG8_STAGE(PG8_SB(0, 0), cB, voffB); PG8_STAGE(PG8_SB(0, 1), cB + hsB, voffB); PG8_STAGE(PG8_SA(0, 0), cA, voffA); PG8_STAGE(PG8_SA(0, 1), cA + hsA, voffA);
;         if (wr == 1) PG8_BAR;
;         PG8_WAIT_V(2); PG8_BAR;
;         PG8_STAGE(PG8_SB(1, 0), cB + kstep, voffB); PG8_STAGE(PG8_SA(1, 0), cA + kstep, voffA); PG8_STAGE(PG8_SB(1, 1), cB + hsB + kstep, voffB);
;         PG8_WAIT_V(6); PG8_BAR;
.LBB0_279:
	v_readlane_b32 s16, v255, 14
	v_readlane_b32 s17, v255, 15
	s_lshl_b32 s84, s16, 11
	s_lshl_b64 s[16:17], s[84:85], 2
	s_add_u32 s11, s72, s16
	s_addc_u32 s13, s73, s17
	v_bfe_u32 v163, v0, 4, 2
	s_add_u32 s16, s11, 0x208000
	v_and_b32_e32 v162, 15, v0
	v_lshlrev_b32_e32 v2, 4, v163
	v_lshlrev_b32_e32 v0, 2, v0
	s_addc_u32 s17, s13, 0
	s_lshl_b32 s84, s7, 6
	v_lshl_or_b32 v2, v162, 6, v2
	s_lshl_b32 s7, s7, 13
	v_and_b32_e32 v0, 32, v0
	v_bitop3_b32 v4, v2, s7, v0 bitop3:0xde
	s_lshl_b32 s7, s18, 5
	s_and_b32 s82, s7, 0x60
	s_lshl_b32 s7, s82, 7
	s_add_i32 s91, s40, 0x18000
	s_add_u32 s18, s8, 0x80
	s_waitcnt vmcnt(2)
	s_barrier
	s_addc_u32 s19, s9, 0
	s_mov_b32 m0, s91
	s_nop 0
	global_load_lds_dwordx4 v159, s[18:19]
	s_add_i32 s64, s40, 0x1a000
	s_add_i32 s33, s40, 0x8000
	s_mov_b32 m0, s64
	s_nop 0
	global_load_lds_dwordx4 v161, s[18:19]
	s_add_u32 s18, s30, 0x80
	s_addc_u32 s19, s31, 0
	s_mov_b32 m0, s33
	s_nop 0
	global_load_lds_dwordx4 v158, s[18:19]
	s_add_i32 s69, s40, 0xa000
	s_add_i32 s67, s40, 0x1c000
	s_mov_b32 m0, s69
	s_nop 0
	global_load_lds_dwordx4 v160, s[18:19]
	s_add_u32 s18, s8, 0x80080
	s_addc_u32 s19, s9, 0
	s_mov_b32 m0, s67
	s_nop 0
	global_load_lds_dwordx4 v159, s[18:19]
	s_add_i32 s53, s40, 0x1e000
	s_mov_b32 m0, s53
	s_nop 0
	global_load_lds_dwordx4 v161, s[18:19]
	v_bitop3_b32 v5, v2, s7, v0 bitop3:0xde
	s_waitcnt vmcnt(6)
	s_add_i32 s52, s40, 0xc000
	v_mov_b32_e32 v2, v1
	v_mov_b32_e32 v3, v1
	s_cmpk_lt_u32 s6, 0x100
	v_mov_b32_e32 v0, v1
	v_add_u32_e32 v164, 0, v5
	v_add_u32_e32 v165, 0, v4
	v_mov_b64_e32 v[10:11], v[2:3]
	v_mov_b64_e32 v[6:7], v[2:3]
	v_mov_b64_e32 v[30:31], v[2:3]
	v_mov_b64_e32 v[34:35], v[2:3]
	v_mov_b64_e32 v[54:55], v[2:3]
	v_mov_b64_e32 v[58:59], v[2:3]
	v_mov_b64_e32 v[70:71], v[2:3]
	s_waitcnt vmcnt(0)
	v_mov_b64_e32 v[74:75], v[2:3]
	v_mov_b64_e32 v[18:19], v[2:3]
	v_mov_b64_e32 v[14:15], v[2:3]
	v_mov_b64_e32 v[42:43], v[2:3]
	v_mov_b64_e32 v[46:47], v[2:3]
	v_mov_b64_e32 v[62:63], v[2:3]
	v_mov_b64_e32 v[66:67], v[2:3]
	v_mov_b64_e32 v[78:79], v[2:3]
	v_mov_b64_e32 v[82:83], v[2:3]
	v_mov_b64_e32 v[86:87], v[2:3]
	v_mov_b64_e32 v[90:91], v[2:3]
	v_mov_b64_e32 v[102:103], v[2:3]
	v_mov_b64_e32 v[106:107], v[2:3]
	v_mov_b64_e32 v[118:119], v[2:3]
	v_mov_b64_e32 v[122:123], v[2:3]
	v_mov_b64_e32 v[134:135], v[2:3]
	v_mov_b64_e32 v[138:139], v[2:3]
	v_mov_b64_e32 v[94:95], v[2:3]
	v_mov_b64_e32 v[98:99], v[2:3]
	v_mov_b64_e32 v[110:111], v[2:3]
	v_mov_b64_e32 v[114:115], v[2:3]
	v_mov_b64_e32 v[126:127], v[2:3]
	v_mov_b64_e32 v[130:131], v[2:3]
	v_mov_b64_e32 v[142:143], v[2:3]
	v_mov_b64_e32 v[146:147], v[2:3]
	s_cselect_b64 s[18:19], -1, 0
	s_add_i32 s44, s40, 0xe000
	s_mov_b32 s34, 0
	v_mov_b64_e32 v[8:9], v[0:1]
	v_mov_b64_e32 v[4:5], v[0:1]
	v_mov_b64_e32 v[28:29], v[0:1]
	v_mov_b64_e32 v[32:33], v[0:1]
	v_mov_b64_e32 v[52:53], v[0:1]
	v_mov_b64_e32 v[56:57], v[0:1]
	v_mov_b64_e32 v[68:69], v[0:1]
	v_mov_b64_e32 v[72:73], v[0:1]
	v_mov_b64_e32 v[16:17], v[0:1]
	v_mov_b64_e32 v[12:13], v[0:1]
	v_mov_b64_e32 v[40:41], v[0:1]
	v_mov_b64_e32 v[44:45], v[0:1]
	v_mov_b64_e32 v[60:61], v[0:1]
	v_mov_b64_e32 v[64:65], v[0:1]
	v_mov_b64_e32 v[76:77], v[0:1]
	v_mov_b64_e32 v[80:81], v[0:1]
	v_mov_b64_e32 v[84:85], v[0:1]
	v_mov_b64_e32 v[88:89], v[0:1]
	v_mov_b64_e32 v[100:101], v[0:1]
	v_mov_b64_e32 v[104:105], v[0:1]
	v_mov_b64_e32 v[116:117], v[0:1]
	v_mov_b64_e32 v[120:121], v[0:1]
	v_mov_b64_e32 v[132:133], v[0:1]
	v_mov_b64_e32 v[136:137], v[0:1]
	v_mov_b64_e32 v[92:93], v[0:1]
	v_mov_b64_e32 v[96:97], v[0:1]
	v_mov_b64_e32 v[108:109], v[0:1]
	v_mov_b64_e32 v[112:113], v[0:1]
	v_mov_b64_e32 v[124:125], v[0:1]
	v_mov_b64_e32 v[128:129], v[0:1]
	v_mov_b64_e32 v[140:141], v[0:1]
	v_mov_b64_e32 v[144:145], v[0:1]
	s_mov_b64 s[62:63], s[88:89]
	s_barrier
	s_getreg_b32 s100, hwreg(HW_REG_HW_ID, 0, 6)
	s_lshl_b32 s100, s100, 2
	s_add_i32 s100, s100, 0x20540
	v_mov_b32_e32 v251, s100
	ds_read_b32 v251, v251
	s_waitcnt lgkmcnt(0)
	v_readfirstlane_b32 s100, v251
	s_cmp_ge_u32 s100, 4
	s_cbranch_scc1 statprio_skip0
	s_setprio 1

; __device__ __forceinline__ int mk_tid() { return mk_wave() * 64 + mk_lane(); }
;     __host__ __device__ bool next(int i, Unit& u) const { return StaticOrder::next(i >> 1, u); }
; template <class Epi, class Sched, bool ALIGN_EPI = false, bool SP2 = false>
; __device__ __forceinline__ void gemm_phase(PG8_LAS unsigned char* lds, const Gemm g, const Sched& S, const Epi& E) {
;     int tid_ = mk_tid(); asm volatile("" : "+v"(tid_));
;     const int tid = tid_, wid = __builtin_amdgcn_readfirstlane(tid >> 6), lane = tid & 63, wr = wid >> 2, wc = wid & 3, fr = lane & 15, fq = lane >> 4;
;     const int K = g.K, nt = K / BK;
;     unsigned voffA[2], voffB[2];
; #pragma unroll
;     for (int i = 0; i < 2; ++i) { int R, C; stage_rc(tid * 16 + i * 8192, R, C); const int Rb = Epi::PERM ? ((R & ~31) + perm32(R & 31)) : R;
;         voffA[i] = (unsigned)(R * g.lda + C) * 2u; voffB[i] = (unsigned)(Rb * g.ldb + C) * 2u; }
;     const size_t kstep = (size_t)(BK * 2);
;     const size_t hsA = (size_t)HALF * g.lda * 2, hsB = (size_t)HALF * g.ldb * 2;
;     const size_t tsA = 2 * hsA, tsB = 2 * hsB;
;     const unsigned ldsbase = (unsigned)(unsigned long long)lds;
;     const unsigned ldsw = (unsigned)wid * 1024u;
;     const int aoff = lds_byte(wr * 64 + fr, fq * 8), boff = lds_byte(wc * 32 + fr, fq * 8);
;     ...
;     Unit cur, nxt; int ui = 0; bool epi_ran = false;
;     if (!S.next(0, cur)) return;
;     f32x4 acc[2][2][4][2];
; #pragma unroll
;     for (int a = 0; a < 2; ++a)
; #pragma unroll
;         for (int b = 0; b < 2; ++b)
; #pragma unroll
;             for (int m = 0; m < 4; ++m)
; #pragma unroll
;                 for (int n = 0; n < 2; ++n) acc[a][b][m][n] = (f32x4){0.f, 0.f, 0.f, 0.f};
;     bf16x8 At[4][2], B0[2][2], B1[2][2];
;     const char* cA = (const char*)g.A + (size_t)cur.pm * tsA + (size_t)cur.k0 * 2; const char* cB = (const char*)g.Bt + (size_t)cur.pn * tsB + (size_t)cur.k0 * 2;
;     S.a_ready(cur);
;     if constexpr (SP2) {
;         PG8_STAGE(PG8_SB(0, 0), cB, voffB); PG8_STAGE(PG8_SB(0, 1), cB + hsB, voffB); PG8_STAGE(PG8_SA(0, 0), cA, voffA); PG8_STAGE(PG8_SA(0, 1), cA + hsA, voffA);
;         if (wr == 1) PG8_BAR;
;         PG8_WAIT_V(2); PG8_BAR;
;         PG8_STAGE(PG8_SB(1, 0), cB + kstep, voffB); PG8_STAGE(PG8_SA(1, 0), cA + kstep, voffA); PG8_STAGE(PG8_SB(1, 1), cB + hsB + kstep, voffB);
;         PG8_WAIT_V(6); PG8_BAR;
.LBB0_638:
	v_bfe_u32 v175, v0, 4, 2
	s_add_u32 s12, s72, 0x204000
	v_and_b32_e32 v174, 15, v0
	v_lshlrev_b32_e32 v2, 4, v175
	v_lshlrev_b32_e32 v0, 2, v0
	s_addc_u32 s13, s73, 0
	s_and_b32 s9, s14, 3
	v_lshl_or_b32 v2, v174, 6, v2
	s_lshl_b32 s14, s15, 13
	v_and_b32_e32 v0, 32, v0
	s_lshl_b32 s69, s15, 6
	v_bitop3_b32 v4, v2, s14, v0 bitop3:0xde
	s_lshl_b32 s78, s9, 5
	s_lshl_b32 s14, s9, 12
	v_bitop3_b32 v5, v2, s14, v0 bitop3:0xde
	s_add_u32 s14, s72, 0x200000
	s_addc_u32 s15, s73, 0
	s_add_i32 s79, s33, 0x18000
	s_add_u32 s18, s6, 0x80
	s_waitcnt vmcnt(2)
	s_barrier
	s_addc_u32 s19, s7, 0
	s_mov_b32 m0, s79
	s_nop 0
	global_load_lds_dwordx4 v171, s[18:19]
	s_add_i32 s82, s33, 0x1a000
	s_add_i32 s84, s33, 0x8000
	s_mov_b32 m0, s82
	s_nop 0
	global_load_lds_dwordx4 v173, s[18:19]
	s_add_u32 s18, s30, 0x80
	s_addc_u32 s19, s31, 0
	s_mov_b32 m0, s84
	s_nop 0
	global_load_lds_dwordx4 v170, s[18:19]
	s_add_i32 s91, s33, 0xa000
	s_add_i32 s80, s33, 0x1c000
	s_mov_b32 m0, s91
	s_nop 0
	global_load_lds_dwordx4 v172, s[18:19]
	s_add_u32 s18, s6, 0x80080
	s_addc_u32 s19, s7, 0
	s_mov_b32 m0, s80
	s_nop 0
	global_load_lds_dwordx4 v171, s[18:19]
	s_add_i32 s81, s33, 0x1e000
	s_add_i32 s83, s33, 0xc000
	s_mov_b32 m0, s81
	s_nop 0
	global_load_lds_dwordx4 v173, s[18:19]
	s_cmpk_lt_u32 s16, 0x100
	s_waitcnt vmcnt(6)
	s_cselect_b64 s[16:17], -1, 0
	s_and_b32 s51, s78, 32
	v_mov_b32_e32 v2, v1
	v_mov_b32_e32 v3, v1
	s_cmp_gt_u32 s9, 1
	v_mov_b32_e32 v0, v1
	v_add_u32_e32 v176, 0, v5
	v_add_u32_e32 v177, 0, v4
	v_mov_b64_e32 v[14:15], v[2:3]
	v_mov_b64_e32 v[18:19], v[2:3]
	v_mov_b64_e32 v[30:31], v[2:3]
	v_mov_b64_e32 v[34:35], v[2:3]
	v_mov_b64_e32 v[46:47], v[2:3]
	v_mov_b64_e32 v[50:51], v[2:3]
	v_mov_b64_e32 v[62:63], v[2:3]
	v_mov_b64_e32 v[66:67], v[2:3]
	v_mov_b64_e32 v[6:7], v[2:3]
	v_mov_b64_e32 v[10:11], v[2:3]
	v_mov_b64_e32 v[22:23], v[2:3]
	v_mov_b64_e32 v[26:27], v[2:3]
	v_mov_b64_e32 v[38:39], v[2:3]
	v_mov_b64_e32 v[42:43], v[2:3]
	v_mov_b64_e32 v[54:55], v[2:3]
	v_mov_b64_e32 v[58:59], v[2:3]
	v_mov_b64_e32 v[78:79], v[2:3]
	v_mov_b64_e32 v[82:83], v[2:3]
	v_mov_b64_e32 v[94:95], v[2:3]
	v_mov_b64_e32 v[98:99], v[2:3]
	v_mov_b64_e32 v[110:111], v[2:3]
	v_mov_b64_e32 v[114:115], v[2:3]
	v_mov_b64_e32 v[126:127], v[2:3]
	v_mov_b64_e32 v[130:131], v[2:3]
	v_mov_b64_e32 v[70:71], v[2:3]
	v_mov_b64_e32 v[74:75], v[2:3]
	v_mov_b64_e32 v[86:87], v[2:3]
	v_mov_b64_e32 v[90:91], v[2:3]
	v_mov_b64_e32 v[102:103], v[2:3]
	v_mov_b64_e32 v[106:107], v[2:3]
	v_mov_b64_e32 v[118:119], v[2:3]
	v_mov_b64_e32 v[122:123], v[2:3]
	s_cselect_b64 s[18:19], -1, 0
	s_add_i32 s57, s33, 0xe000
	s_mov_b32 s36, 0
	v_mov_b64_e32 v[12:13], v[0:1]
	v_mov_b64_e32 v[16:17], v[0:1]
	v_mov_b64_e32 v[28:29], v[0:1]
	v_mov_b64_e32 v[32:33], v[0:1]
	v_mov_b64_e32 v[44:45], v[0:1]
	v_mov_b64_e32 v[48:49], v[0:1]
	v_mov_b64_e32 v[60:61], v[0:1]
	v_mov_b64_e32 v[64:65], v[0:1]
	v_mov_b64_e32 v[4:5], v[0:1]
	v_mov_b64_e32 v[8:9], v[0:1]
	v_mov_b64_e32 v[20:21], v[0:1]
	v_mov_b64_e32 v[24:25], v[0:1]
	v_mov_b64_e32 v[36:37], v[0:1]
	v_mov_b64_e32 v[40:41], v[0:1]
	v_mov_b64_e32 v[52:53], v[0:1]
	v_mov_b64_e32 v[56:57], v[0:1]
	v_mov_b64_e32 v[76:77], v[0:1]
	v_mov_b64_e32 v[80:81], v[0:1]
	v_mov_b64_e32 v[92:93], v[0:1]
	v_mov_b64_e32 v[96:97], v[0:1]
	v_mov_b64_e32 v[108:109], v[0:1]
	v_mov_b64_e32 v[112:113], v[0:1]
	v_mov_b64_e32 v[124:125], v[0:1]
	v_mov_b64_e32 v[128:129], v[0:1]
	v_mov_b64_e32 v[68:69], v[0:1]
	v_mov_b64_e32 v[72:73], v[0:1]
	v_mov_b64_e32 v[84:85], v[0:1]
	v_mov_b64_e32 v[88:89], v[0:1]
	v_mov_b64_e32 v[100:101], v[0:1]
	v_mov_b64_e32 v[104:105], v[0:1]
	v_mov_b64_e32 v[116:117], v[0:1]
	v_mov_b64_e32 v[120:121], v[0:1]
	s_barrier
	s_getreg_b32 s100, hwreg(HW_REG_HW_ID, 0, 6)
	s_lshl_b32 s100, s100, 2
	s_add_i32 s100, s100, 0x20540
	v_mov_b32_e32 v251, s100
	ds_read_b32 v251, v251
	s_waitcnt lgkmcnt(0)
	v_readfirstlane_b32 s100, v251
	s_cmp_ge_u32 s100, 4
	s_cbranch_scc1 statprio_skip1
	s_setprio 1

; __device__ __forceinline__ int mk_tid() { return mk_wave() * 64 + mk_lane(); }
;     __host__ __device__ bool next(int i, Unit& u) const { return StaticOrder::next(i >> 1, u); }
; template <class Epi, class Sched, bool ALIGN_EPI = false, bool SP2 = false>
; __device__ __forceinline__ void gemm_phase(PG8_LAS unsigned char* lds, const Gemm g, const Sched& S, const Epi& E) {
;     int tid_ = mk_tid(); asm volatile("" : "+v"(tid_));
;     const int tid = tid_, wid = __builtin_amdgcn_readfirstlane(tid >> 6), lane = tid & 63, wr = wid >> 2, wc = wid & 3, fr = lane & 15, fq = lane >> 4;
;     const int K = g.K, nt = K / BK;
;     unsigned voffA[2], voffB[2];
; #pragma unroll
;     for (int i = 0; i < 2; ++i) { int R, C; stage_rc(tid * 16 + i * 8192, R, C); const int Rb = Epi::PERM ? ((R & ~31) + perm32(R & 31)) : R;
;         voffA[i] = (unsigned)(R * g.lda + C) * 2u; voffB[i] = (unsigned)(Rb * g.ldb + C) * 2u; }
;     const size_t kstep = (size_t)(BK * 2);
;     const size_t hsA = (size_t)HALF * g.lda * 2, hsB = (size_t)HALF * g.ldb * 2;
;     const size_t tsA = 2 * hsA, tsB = 2 * hsB;
;     const unsigned ldsbase = (unsigned)(unsigned long long)lds;
;     const unsigned ldsw = (unsigned)wid * 1024u;
;     const int aoff = lds_byte(wr * 64 + fr, fq * 8), boff = lds_byte(wc * 32 + fr, fq * 8);
;     ...
;     Unit cur, nxt; int ui = 0; bool epi_ran = false;
;     if (!S.next(0, cur)) return;
;     f32x4 acc[2][2][4][2];
; #pragma unroll
;     for (int a = 0; a < 2; ++a)
; #pragma unroll
;         for (int b = 0; b < 2; ++b)
; #pragma unroll
;             for (int m = 0; m < 4; ++m)
; #pragma unroll
;                 for (int n = 0; n < 2; ++n) acc[a][b][m][n] = (f32x4){0.f, 0.f, 0.f, 0.f};
;     bf16x8 At[4][2], B0[2][2], B1[2][2];
;     const char* cA = (const char*)g.A + (size_t)cur.pm * tsA + (size_t)cur.k0 * 2; const char* cB = (const char*)g.Bt + (size_t)cur.pn * tsB + (size_t)cur.k0 * 2;
;     S.a_ready(cur);
;     if constexpr (SP2) {
;         PG8_STAGE(PG8_SB(0, 0), cB, voffB); PG8_STAGE(PG8_SB(0, 1), cB + hsB, voffB); PG8_STAGE(PG8_SA(0, 0), cA, voffA); PG8_STAGE(PG8_SA(0, 1), cA + hsA, voffA);
;         if (wr == 1) PG8_BAR;
;         PG8_WAIT_V(2); PG8_BAR;
;         PG8_STAGE(PG8_SB(1, 0), cB + kstep, voffB); PG8_STAGE(PG8_SA(1, 0), cA + kstep, voffA); PG8_STAGE(PG8_SB(1, 1), cB + hsB + kstep, voffB);
;         PG8_WAIT_V(6); PG8_BAR;
.LBB0_918:
	s_add_u32 s40, s86, 0x4000
	v_lshrrev_b32_e32 v3, 1, v0
	s_addc_u32 s41, s87, 0
	v_and_b32_e32 v3, 24, v3
	s_lshl_b32 s6, s6, 5
	v_and_b32_e32 v2, 15, v0
	v_lshlrev_b32_e32 v4, 1, v3
	v_lshlrev_b32_e32 v0, 2, v0
	s_and_b32 s8, s6, 0x60
	v_lshl_or_b32 v184, s7, 6, v2
	v_lshl_or_b32 v2, v2, 6, v4
	s_lshl_b32 s7, s7, 13
	v_and_b32_e32 v0, 32, v0
	s_lshl_b32 s6, s8, 7
	s_add_i32 s44, s27, 0x18000
	v_bitop3_b32 v5, v2, s6, v0 bitop3:0xde
	s_add_u32 s6, s18, 0x80
	v_bitop3_b32 v4, v2, s7, v0 bitop3:0xde
	s_waitcnt vmcnt(2)
	s_barrier
	s_addc_u32 s7, s19, 0
	s_mov_b32 m0, s44
	s_nop 0
	global_load_lds_dwordx4 v175, s[6:7]
	s_add_i32 s48, s27, 0x1a000
	s_add_i32 s49, s27, 0x8000
	s_mov_b32 m0, s48
	s_nop 0
	global_load_lds_dwordx4 v177, s[6:7]
	s_add_u32 s6, s20, 0x80
	s_addc_u32 s7, s21, 0
	s_mov_b32 m0, s49
	s_nop 0
	global_load_lds_dwordx4 v174, s[6:7]
	s_add_i32 s51, s27, 0xa000
	s_add_i32 s52, s27, 0x1c000
	s_mov_b32 m0, s51
	s_nop 0
	global_load_lds_dwordx4 v176, s[6:7]
	s_add_u32 s6, s18, 0x80080
	s_addc_u32 s7, s19, 0
	s_mov_b32 m0, s52
	s_nop 0
	global_load_lds_dwordx4 v175, s[6:7]
	s_add_i32 s53, s27, 0x1e000
	s_mov_b32 m0, s53
	s_nop 0
	global_load_lds_dwordx4 v177, s[6:7]
	v_readlane_b32 s6, v255, 8
	s_waitcnt vmcnt(6)
	v_or_b32_e32 v185, s8, v3
	v_mov_b32_e32 v2, v1
	v_mov_b32_e32 v3, v1
	v_readlane_b32 s7, v255, 9
	v_mov_b32_e32 v0, v1
	v_add_u32_e32 v186, 0, v5
	v_add_u32_e32 v187, 0, v4
	v_mov_b64_e32 v[6:7], v[2:3]
	v_mov_b64_e32 v[10:11], v[2:3]
	v_mov_b64_e32 v[22:23], v[2:3]
	v_mov_b64_e32 v[26:27], v[2:3]
	v_mov_b64_e32 v[38:39], v[2:3]
	v_mov_b64_e32 v[42:43], v[2:3]
	v_mov_b64_e32 v[54:55], v[2:3]
	v_mov_b64_e32 v[58:59], v[2:3]
	v_mov_b64_e32 v[14:15], v[2:3]
	v_mov_b64_e32 v[18:19], v[2:3]
	v_mov_b64_e32 v[30:31], v[2:3]
	v_mov_b64_e32 v[34:35], v[2:3]
	v_mov_b64_e32 v[46:47], v[2:3]
	v_mov_b64_e32 v[50:51], v[2:3]
	v_mov_b64_e32 v[62:63], v[2:3]
	v_mov_b64_e32 v[66:67], v[2:3]
	v_mov_b64_e32 v[70:71], v[2:3]
	v_mov_b64_e32 v[74:75], v[2:3]
	v_mov_b64_e32 v[86:87], v[2:3]
	v_mov_b64_e32 v[90:91], v[2:3]
	v_mov_b64_e32 v[102:103], v[2:3]
	v_mov_b64_e32 v[106:107], v[2:3]
	v_mov_b64_e32 v[134:135], v[2:3]
	v_mov_b64_e32 v[138:139], v[2:3]
	v_mov_b64_e32 v[78:79], v[2:3]
	v_mov_b64_e32 v[82:83], v[2:3]
	v_mov_b64_e32 v[94:95], v[2:3]
	v_mov_b64_e32 v[98:99], v[2:3]
	v_mov_b64_e32 v[110:111], v[2:3]
	v_mov_b64_e32 v[118:119], v[2:3]
	v_mov_b64_e32 v[142:143], v[2:3]
	v_mov_b64_e32 v[146:147], v[2:3]
	s_mov_b32 s67, s6
	v_readlane_b32 s6, v255, 4
	s_add_i32 s57, s27, 0xc000
	s_add_i32 s63, s27, 0xe000
	s_mov_b32 s22, 0
	v_mov_b64_e32 v[4:5], v[0:1]
	v_mov_b64_e32 v[8:9], v[0:1]
	v_mov_b64_e32 v[20:21], v[0:1]
	v_mov_b64_e32 v[24:25], v[0:1]
	v_mov_b64_e32 v[36:37], v[0:1]
	v_mov_b64_e32 v[40:41], v[0:1]
	v_mov_b64_e32 v[52:53], v[0:1]
	v_mov_b64_e32 v[56:57], v[0:1]
	v_mov_b64_e32 v[12:13], v[0:1]
	v_mov_b64_e32 v[16:17], v[0:1]
	v_mov_b64_e32 v[28:29], v[0:1]
	v_mov_b64_e32 v[32:33], v[0:1]
	v_mov_b64_e32 v[44:45], v[0:1]
	v_mov_b64_e32 v[48:49], v[0:1]
	v_mov_b64_e32 v[60:61], v[0:1]
	v_mov_b64_e32 v[64:65], v[0:1]
	v_mov_b64_e32 v[68:69], v[0:1]
	v_mov_b64_e32 v[72:73], v[0:1]
	v_mov_b64_e32 v[84:85], v[0:1]
	v_mov_b64_e32 v[88:89], v[0:1]
	v_mov_b64_e32 v[100:101], v[0:1]
	v_mov_b64_e32 v[104:105], v[0:1]
	v_mov_b64_e32 v[132:133], v[0:1]
	v_mov_b64_e32 v[136:137], v[0:1]
	v_mov_b64_e32 v[76:77], v[0:1]
	v_mov_b64_e32 v[80:81], v[0:1]
	v_mov_b64_e32 v[92:93], v[0:1]
	v_mov_b64_e32 v[96:97], v[0:1]
	v_mov_b64_e32 v[108:109], v[0:1]
	v_mov_b64_e32 v[116:117], v[0:1]
	v_mov_b64_e32 v[140:141], v[0:1]
	v_mov_b64_e32 v[144:145], v[0:1]
	s_mov_b32 s69, s6
	s_barrier
	v_readlane_b32 s7, v255, 5
	s_getreg_b32 s100, hwreg(HW_REG_HW_ID, 0, 6)
	s_lshl_b32 s100, s100, 2
	s_add_i32 s100, s100, 0x20540
	v_mov_b32_e32 v251, s100
	ds_read_b32 v251, v251
	s_waitcnt lgkmcnt(0)
	v_readfirstlane_b32 s100, v251
	s_cmp_ge_u32 s100, 4
	s_cbranch_scc1 statprio_skip2
	s_setprio 1

; __device__ __forceinline__ int mk_tid() { return mk_wave() * 64 + mk_lane(); }
;     __host__ __device__ bool next(int i, Unit& u) const { return StaticOrder::next(i >> 1, u); }
; template <class Epi, class Sched, bool ALIGN_EPI = false, bool SP2 = false>
; __device__ __forceinline__ void gemm_phase(PG8_LAS unsigned char* lds, const Gemm g, const Sched& S, const Epi& E) {
;     int tid_ = mk_tid(); asm volatile("" : "+v"(tid_));
;     const int tid = tid_, wid = __builtin_amdgcn_readfirstlane(tid >> 6), lane = tid & 63, wr = wid >> 2, wc = wid & 3, fr = lane & 15, fq = lane >> 4;
;     const int K = g.K, nt = K / BK;
;     unsigned voffA[2], voffB[2];
; #pragma unroll
;     for (int i = 0; i < 2; ++i) { int R, C; stage_rc(tid * 16 + i * 8192, R, C); const int Rb = Epi::PERM ? ((R & ~31) + perm32(R & 31)) : R;
;         voffA[i] = (unsigned)(R * g.lda + C) * 2u; voffB[i] = (unsigned)(Rb * g.ldb + C) * 2u; }
;     const size_t kstep = (size_t)(BK * 2);
;     const size_t hsA = (size_t)HALF * g.lda * 2, hsB = (size_t)HALF * g.ldb * 2;
;     const size_t tsA = 2 * hsA, tsB = 2 * hsB;
;     const unsigned ldsbase = (unsigned)(unsigned long long)lds;
;     const unsigned ldsw = (unsigned)wid * 1024u;
;     const int aoff = lds_byte(wr * 64 + fr, fq * 8), boff = lds_byte(wc * 32 + fr, fq * 8);
;     ...
;     Unit cur, nxt; int ui = 0; bool epi_ran = false;
;     if (!S.next(0, cur)) return;
;     f32x4 acc[2][2][4][2];
; #pragma unroll
;     for (int a = 0; a < 2; ++a)
; #pragma unroll
;         for (int b = 0; b < 2; ++b)
; #pragma unroll
;             for (int m = 0; m < 4; ++m)
; #pragma unroll
;                 for (int n = 0; n < 2; ++n) acc[a][b][m][n] = (f32x4){0.f, 0.f, 0.f, 0.f};
;     bf16x8 At[4][2], B0[2][2], B1[2][2];
;     const char* cA = (const char*)g.A + (size_t)cur.pm * tsA + (size_t)cur.k0 * 2; const char* cB = (const char*)g.Bt + (size_t)cur.pn * tsB + (size_t)cur.k0 * 2;
;     S.a_ready(cur);
;     if constexpr (SP2) {
;         PG8_STAGE(PG8_SB(0, 0), cB, voffB); PG8_STAGE(PG8_SB(0, 1), cB + hsB, voffB); PG8_STAGE(PG8_SA(0, 0), cA, voffA); PG8_STAGE(PG8_SA(0, 1), cA + hsA, voffA);
;         if (wr == 1) PG8_BAR;
;         PG8_WAIT_V(2); PG8_BAR;
;         PG8_STAGE(PG8_SB(1, 0), cB + kstep, voffB); PG8_STAGE(PG8_SA(1, 0), cA + kstep, voffA); PG8_STAGE(PG8_SB(1, 1), cB + hsB + kstep, voffB);
;         PG8_WAIT_V(6); PG8_BAR;
.LBB0_942:
	v_bfe_u32 v2, v0, 4, 2
	s_add_u32 s51, s72, 0x58400000
	v_and_b32_e32 v3, 15, v0
	v_lshlrev_b32_e32 v5, 4, v2
	v_lshlrev_b32_e32 v0, 2, v0
	s_addc_u32 s52, s73, 0
	v_lshl_or_b32 v4, s7, 6, v3
	v_lshl_or_b32 v3, v3, 6, v5
	s_lshl_b32 s7, s7, 13
	v_and_b32_e32 v0, 32, v0
	v_bitop3_b32 v5, v3, s7, v0 bitop3:0xde
	s_lshl_b32 s7, s8, 5
	s_and_b32 s14, s7, 0x60
	s_lshl_b32 s7, s14, 7
	s_add_i32 s53, s35, 0x18000
	s_add_u32 s8, s24, 0x80
	s_waitcnt vmcnt(2)
	s_barrier
	s_addc_u32 s9, s25, 0
	s_mov_b32 m0, s53
	s_nop 0
	global_load_lds_dwordx4 v130, s[8:9]
	s_add_i32 s57, s35, 0x1a000
	s_add_i32 s63, s35, 0x8000
	s_mov_b32 m0, s57
	s_nop 0
	global_load_lds_dwordx4 v131, s[8:9]
	s_add_u32 s8, s26, 0x80
	s_addc_u32 s9, s27, 0
	s_mov_b32 m0, s63
	s_nop 0
	global_load_lds_dwordx4 v130, s[8:9]
	s_add_i32 s64, s35, 0xa000
	s_add_i32 s67, s35, 0x1c000
	s_mov_b32 m0, s64
	s_nop 0
	global_load_lds_dwordx4 v131, s[8:9]
	s_add_u32 s8, s24, 0x80080
	s_addc_u32 s9, s25, 0
	s_mov_b32 m0, s67
	s_nop 0
	global_load_lds_dwordx4 v130, s[8:9]
	s_add_i32 s69, s35, 0x1e000
	s_mov_b32 m0, s69
	s_nop 0
	global_load_lds_dwordx4 v131, s[8:9]
	v_bitop3_b32 v3, v3, s7, v0 bitop3:0xde
	s_waitcnt vmcnt(6)
	s_add_i32 s78, s35, 0xc000
	v_mov_b32_e32 v82, v1
	v_mov_b32_e32 v83, v1
	v_mov_b32_e32 v84, v1
	v_mov_b32_e32 v85, v1
	s_cmpk_lt_u32 s6, 0x100
	v_lshlrev_b32_e32 v0, 2, v2
	v_add_u32_e32 v132, 0xffffc000, v4
	v_add_u32_e32 v133, 0, v3
	v_add_u32_e32 v134, 0, v5
	v_mov_b64_e32 v[96:97], v[84:85]
	v_mov_b64_e32 v[112:113], v[84:85]
	v_mov_b64_e32 v[108:109], v[84:85]
	v_mov_b64_e32 v[120:121], v[84:85]
	v_mov_b64_e32 v[116:117], v[84:85]
	v_mov_b64_e32 v[128:129], v[84:85]
	v_mov_b64_e32 v[124:125], v[84:85]
	v_mov_b64_e32 v[70:71], v[82:83]
	v_mov_b64_e32 v[66:67], v[82:83]
	v_mov_b64_e32 v[78:79], v[82:83]
	v_mov_b64_e32 v[74:75], v[82:83]
	v_mov_b64_e32 v[92:93], v[84:85]
	v_mov_b64_e32 v[88:89], v[84:85]
	v_mov_b64_e32 v[104:105], v[84:85]
	v_mov_b64_e32 v[100:101], v[84:85]
	v_mov_b64_e32 v[38:39], v[82:83]
	v_mov_b64_e32 v[34:35], v[82:83]
	v_mov_b64_e32 v[46:47], v[82:83]
	v_mov_b64_e32 v[42:43], v[82:83]
	v_mov_b64_e32 v[54:55], v[82:83]
	v_mov_b64_e32 v[50:51], v[82:83]
	v_mov_b64_e32 v[62:63], v[82:83]
	v_mov_b64_e32 v[58:59], v[82:83]
	v_mov_b64_e32 v[6:7], v[82:83]
	v_mov_b64_e32 v[2:3], v[82:83]
	v_mov_b64_e32 v[14:15], v[82:83]
	v_mov_b64_e32 v[10:11], v[82:83]
	v_mov_b64_e32 v[22:23], v[82:83]
	v_mov_b64_e32 v[18:19], v[82:83]
	v_mov_b64_e32 v[30:31], v[82:83]
	v_mov_b64_e32 v[26:27], v[82:83]
	v_readlane_b32 s8, v254, 33
	s_cselect_b64 s[12:13], -1, 0
	s_add_i32 s79, s35, 0xe000
	s_mov_b32 s7, 0
	s_lshl_b32 s84, s14, 2
	v_lshlrev_b32_e32 v0, 2, v0
	v_mov_b64_e32 v[94:95], v[82:83]
	v_mov_b64_e32 v[110:111], v[82:83]
	v_mov_b64_e32 v[106:107], v[82:83]
	v_mov_b64_e32 v[118:119], v[82:83]
	v_mov_b64_e32 v[114:115], v[82:83]
	v_mov_b64_e32 v[126:127], v[82:83]
	v_mov_b64_e32 v[122:123], v[82:83]
	v_mov_b64_e32 v[72:73], v[84:85]
	v_mov_b64_e32 v[68:69], v[84:85]
	v_mov_b64_e32 v[80:81], v[84:85]
	v_mov_b64_e32 v[76:77], v[84:85]
	v_mov_b64_e32 v[90:91], v[82:83]
	v_mov_b64_e32 v[86:87], v[82:83]
	v_mov_b64_e32 v[102:103], v[82:83]
	v_mov_b64_e32 v[98:99], v[82:83]
	v_mov_b64_e32 v[40:41], v[84:85]
	v_mov_b64_e32 v[36:37], v[84:85]
	v_mov_b64_e32 v[48:49], v[84:85]
	v_mov_b64_e32 v[44:45], v[84:85]
	v_mov_b64_e32 v[56:57], v[84:85]
	v_mov_b64_e32 v[52:53], v[84:85]
	v_mov_b64_e32 v[64:65], v[84:85]
	v_mov_b64_e32 v[60:61], v[84:85]
	v_mov_b64_e32 v[8:9], v[84:85]
	v_mov_b64_e32 v[4:5], v[84:85]
	v_mov_b64_e32 v[16:17], v[84:85]
	v_mov_b64_e32 v[12:13], v[84:85]
	v_mov_b64_e32 v[24:25], v[84:85]
	v_mov_b64_e32 v[20:21], v[84:85]
	v_mov_b64_e32 v[32:33], v[84:85]
	v_mov_b64_e32 v[28:29], v[84:85]
	v_readlane_b32 s6, v254, 31
	s_mov_b32 s83, s8
	v_readlane_b32 s91, v254, 29
	s_barrier
	v_readlane_b32 s9, v254, 34
	s_getreg_b32 s100, hwreg(HW_REG_HW_ID, 0, 6)
	s_lshl_b32 s100, s100, 2
	s_add_i32 s100, s100, 0x20540
	v_mov_b32_e32 v251, s100
	ds_read_b32 v251, v251
	s_waitcnt lgkmcnt(0)
	v_readfirstlane_b32 s100, v251
	s_cmp_ge_u32 s100, 4
	s_cbranch_scc1 statprio_skip3
	s_setprio 1

; __device__ __forceinline__ int mk_tid() { return mk_wave() * 64 + mk_lane(); }
;     __host__ __device__ bool next(int i, Unit& u) const { return StaticOrder::next(i >> 1, u); }
; template <class Epi, class Sched, bool ALIGN_EPI = false, bool SP2 = false>
; __device__ __forceinline__ void gemm_phase(PG8_LAS unsigned char* lds, const Gemm g, const Sched& S, const Epi& E) {
;     int tid_ = mk_tid(); asm volatile("" : "+v"(tid_));
;     const int tid = tid_, wid = __builtin_amdgcn_readfirstlane(tid >> 6), lane = tid & 63, wr = wid >> 2, wc = wid & 3, fr = lane & 15, fq = lane >> 4;
;     const int K = g.K, nt = K / BK;
;     unsigned voffA[2], voffB[2];
; #pragma unroll
;     for (int i = 0; i < 2; ++i) { int R, C; stage_rc(tid * 16 + i * 8192, R, C); const int Rb = Epi::PERM ? ((R & ~31) + perm32(R & 31)) : R;
;         voffA[i] = (unsigned)(R * g.lda + C) * 2u; voffB[i] = (unsigned)(Rb * g.ldb + C) * 2u; }
;     const size_t kstep = (size_t)(BK * 2);
;     const size_t hsA = (size_t)HALF * g.lda * 2, hsB = (size_t)HALF * g.ldb * 2;
;     const size_t tsA = 2 * hsA, tsB = 2 * hsB;
;     const unsigned ldsbase = (unsigned)(unsigned long long)lds;
;     const unsigned ldsw = (unsigned)wid * 1024u;
;     const int aoff = lds_byte(wr * 64 + fr, fq * 8), boff = lds_byte(wc * 32 + fr, fq * 8);
;     ...
;     Unit cur, nxt; int ui = 0; bool epi_ran = false;
;     if (!S.next(0, cur)) return;
;     f32x4 acc[2][2][4][2];
; #pragma unroll
;     for (int a = 0; a < 2; ++a)
; #pragma unroll
;         for (int b = 0; b < 2; ++b)
; #pragma unroll
;             for (int m = 0; m < 4; ++m)
; #pragma unroll
;                 for (int n = 0; n < 2; ++n) acc[a][b][m][n] = (f32x4){0.f, 0.f, 0.f, 0.f};
;     bf16x8 At[4][2], B0[2][2], B1[2][2];
;     const char* cA = (const char*)g.A + (size_t)cur.pm * tsA + (size_t)cur.k0 * 2; const char* cB = (const char*)g.Bt + (size_t)cur.pn * tsB + (size_t)cur.k0 * 2;
;     S.a_ready(cur);
;     if constexpr (SP2) {
;         PG8_STAGE(PG8_SB(0, 0), cB, voffB); PG8_STAGE(PG8_SB(0, 1), cB + hsB, voffB); PG8_STAGE(PG8_SA(0, 0), cA, voffA); PG8_STAGE(PG8_SA(0, 1), cA + hsA, voffA);
;         if (wr == 1) PG8_BAR;
;         PG8_WAIT_V(2); PG8_BAR;
;         PG8_STAGE(PG8_SB(1, 0), cB + kstep, voffB); PG8_STAGE(PG8_SA(1, 0), cA + kstep, voffA); PG8_STAGE(PG8_SB(1, 1), cB + hsB + kstep, voffB);
;         PG8_WAIT_V(6); PG8_BAR;
.LBB0_1108:
	v_lshrrev_b32_e32 v3, 1, v0
	v_and_b32_e32 v3, 24, v3
	v_and_b32_e32 v2, 15, v0
	v_lshlrev_b32_e32 v4, 1, v3
	v_lshlrev_b32_e32 v0, 2, v0
	v_lshl_or_b32 v136, s7, 6, v2
	v_lshl_or_b32 v2, v2, 6, v4
	s_lshl_b32 s7, s7, 13
	v_and_b32_e32 v0, 32, v0
	v_bitop3_b32 v4, v2, s7, v0 bitop3:0xde
	s_lshl_b32 s7, s10, 5
	s_and_b32 s7, s7, 0x60
	s_lshl_b32 s10, s7, 7
	s_add_i32 s53, s25, 0x18000
	v_bitop3_b32 v5, v2, s10, v0 bitop3:0xde
	s_add_u32 s10, s26, 0x80
	s_waitcnt vmcnt(2)
	s_barrier
	s_addc_u32 s11, s27, 0
	s_mov_b32 m0, s53
	s_nop 0
	global_load_lds_dwordx4 v133, s[10:11]
	s_add_i32 s57, s25, 0x1a000
	s_add_i32 s63, s25, 0x8000
	s_mov_b32 m0, s57
	s_nop 0
	global_load_lds_dwordx4 v135, s[10:11]
	s_add_u32 s10, s28, 0x80
	s_addc_u32 s11, s29, 0
	s_mov_b32 m0, s63
	s_nop 0
	global_load_lds_dwordx4 v132, s[10:11]
	s_add_i32 s64, s25, 0xa000
	s_add_i32 s67, s25, 0x1c000
	s_mov_b32 m0, s64
	s_nop 0
	global_load_lds_dwordx4 v134, s[10:11]
	s_add_u32 s10, s26, 0x80080
	s_addc_u32 s11, s27, 0
	s_mov_b32 m0, s67
	s_nop 0
	global_load_lds_dwordx4 v133, s[10:11]
	s_add_i32 s69, s25, 0x1e000
	s_mov_b32 m0, s69
	s_nop 0
	global_load_lds_dwordx4 v135, s[10:11]
	s_waitcnt vmcnt(6)
	s_add_i32 s77, s25, 0xc000
	v_or_b32_e32 v137, s7, v3
	v_mov_b32_e32 v2, v1
	v_mov_b32_e32 v3, v1
	s_cmpk_lt_u32 s6, 0x100
	v_mov_b32_e32 v0, v1
	v_add_u32_e32 v138, 0, v5
	v_add_u32_e32 v139, 0, v4
	v_mov_b64_e32 v[10:11], v[2:3]
	v_mov_b64_e32 v[18:19], v[2:3]
	v_mov_b64_e32 v[26:27], v[2:3]
	v_mov_b64_e32 v[34:35], v[2:3]
	v_mov_b64_e32 v[42:43], v[2:3]
	v_mov_b64_e32 v[50:51], v[2:3]
	v_mov_b64_e32 v[58:59], v[2:3]
	v_mov_b64_e32 v[74:75], v[2:3]
	v_mov_b64_e32 v[6:7], v[2:3]
	v_mov_b64_e32 v[14:15], v[2:3]
	v_mov_b64_e32 v[22:23], v[2:3]
	v_mov_b64_e32 v[30:31], v[2:3]
	v_mov_b64_e32 v[38:39], v[2:3]
	v_mov_b64_e32 v[46:47], v[2:3]
	v_mov_b64_e32 v[54:55], v[2:3]
	v_mov_b64_e32 v[66:67], v[2:3]
	v_mov_b64_e32 v[70:71], v[2:3]
	v_mov_b64_e32 v[82:83], v[2:3]
	v_mov_b64_e32 v[90:91], v[2:3]
	v_mov_b64_e32 v[98:99], v[2:3]
	v_mov_b64_e32 v[106:107], v[2:3]
	v_mov_b64_e32 v[114:115], v[2:3]
	v_mov_b64_e32 v[122:123], v[2:3]
	v_mov_b64_e32 v[130:131], v[2:3]
	v_mov_b64_e32 v[62:63], v[2:3]
	v_mov_b64_e32 v[78:79], v[2:3]
	v_mov_b64_e32 v[86:87], v[2:3]
	v_mov_b64_e32 v[94:95], v[2:3]
	v_mov_b64_e32 v[102:103], v[2:3]
	v_mov_b64_e32 v[110:111], v[2:3]
	v_mov_b64_e32 v[118:119], v[2:3]
	v_mov_b64_e32 v[126:127], v[2:3]
	s_cselect_b64 s[10:11], -1, 0
	s_add_i32 s78, s25, 0xe000
	s_mov_b32 s23, 0
	v_mov_b64_e32 v[8:9], v[0:1]
	v_mov_b64_e32 v[16:17], v[0:1]
	v_mov_b64_e32 v[24:25], v[0:1]
	v_mov_b64_e32 v[32:33], v[0:1]
	v_mov_b64_e32 v[40:41], v[0:1]
	v_mov_b64_e32 v[48:49], v[0:1]
	v_mov_b64_e32 v[56:57], v[0:1]
	v_mov_b64_e32 v[72:73], v[0:1]
	v_mov_b64_e32 v[4:5], v[0:1]
	v_mov_b64_e32 v[12:13], v[0:1]
	v_mov_b64_e32 v[20:21], v[0:1]
	v_mov_b64_e32 v[28:29], v[0:1]
	v_mov_b64_e32 v[36:37], v[0:1]
	v_mov_b64_e32 v[44:45], v[0:1]
	v_mov_b64_e32 v[52:53], v[0:1]
	v_mov_b64_e32 v[64:65], v[0:1]
	v_mov_b64_e32 v[68:69], v[0:1]
	v_mov_b64_e32 v[80:81], v[0:1]
	v_mov_b64_e32 v[88:89], v[0:1]
	v_mov_b64_e32 v[96:97], v[0:1]
	v_mov_b64_e32 v[104:105], v[0:1]
	v_mov_b64_e32 v[112:113], v[0:1]
	v_mov_b64_e32 v[120:121], v[0:1]
	v_mov_b64_e32 v[128:129], v[0:1]
	v_mov_b64_e32 v[60:61], v[0:1]
	v_mov_b64_e32 v[76:77], v[0:1]
	v_mov_b64_e32 v[84:85], v[0:1]
	v_mov_b64_e32 v[92:93], v[0:1]
	v_mov_b64_e32 v[100:101], v[0:1]
	v_mov_b64_e32 v[108:109], v[0:1]
	v_mov_b64_e32 v[116:117], v[0:1]
	v_mov_b64_e32 v[124:125], v[0:1]
	s_barrier
	s_getreg_b32 s100, hwreg(HW_REG_HW_ID, 0, 6)
	s_lshl_b32 s100, s100, 2
	s_add_i32 s100, s100, 0x20540
	v_mov_b32_e32 v251, s100
	ds_read_b32 v251, v251
	s_waitcnt lgkmcnt(0)
	v_readfirstlane_b32 s100, v251
	s_cmp_ge_u32 s100, 4
	s_cbranch_scc1 statprio_skip4
	s_setprio 1

; __device__ __forceinline__ int mk_tid() { return mk_wave() * 64 + mk_lane(); }
;     __host__ __device__ bool next(int i, Unit& u) const { return StaticOrder::next(i >> 1, u); }
; template <class Epi, class Sched, bool ALIGN_EPI = false, bool SP2 = false>
; __device__ __forceinline__ void gemm_phase(PG8_LAS unsigned char* lds, const Gemm g, const Sched& S, const Epi& E) {
;     int tid_ = mk_tid(); asm volatile("" : "+v"(tid_));
;     const int tid = tid_, wid = __builtin_amdgcn_readfirstlane(tid >> 6), lane = tid & 63, wr = wid >> 2, wc = wid & 3, fr = lane & 15, fq = lane >> 4;
;     const int K = g.K, nt = K / BK;
;     unsigned voffA[2], voffB[2];
; #pragma unroll
;     for (int i = 0; i < 2; ++i) { int R, C; stage_rc(tid * 16 + i * 8192, R, C); const int Rb = Epi::PERM ? ((R & ~31) + perm32(R & 31)) : R;
;         voffA[i] = (unsigned)(R * g.lda + C) * 2u; voffB[i] = (unsigned)(Rb * g.ldb + C) * 2u; }
;     const size_t kstep = (size_t)(BK * 2);
;     const size_t hsA = (size_t)HALF * g.lda * 2, hsB = (size_t)HALF * g.ldb * 2;
;     const size_t tsA = 2 * hsA, tsB = 2 * hsB;
;     const unsigned ldsbase = (unsigned)(unsigned long long)lds;
;     const unsigned ldsw = (unsigned)wid * 1024u;
;     const int aoff = lds_byte(wr * 64 + fr, fq * 8), boff = lds_byte(wc * 32 + fr, fq * 8);
;     ...
;     Unit cur, nxt; int ui = 0; bool epi_ran = false;
;     if (!S.next(0, cur)) return;
;     f32x4 acc[2][2][4][2];
; #pragma unroll
;     for (int a = 0; a < 2; ++a)
; #pragma unroll
;         for (int b = 0; b < 2; ++b)
; #pragma unroll
;             for (int m = 0; m < 4; ++m)
; #pragma unroll
;                 for (int n = 0; n < 2; ++n) acc[a][b][m][n] = (f32x4){0.f, 0.f, 0.f, 0.f};
;     bf16x8 At[4][2], B0[2][2], B1[2][2];
;     const char* cA = (const char*)g.A + (size_t)cur.pm * tsA + (size_t)cur.k0 * 2; const char* cB = (const char*)g.Bt + (size_t)cur.pn * tsB + (size_t)cur.k0 * 2;
;     S.a_ready(cur);
;     if constexpr (SP2) {
;         PG8_STAGE(PG8_SB(0, 0), cB, voffB); PG8_STAGE(PG8_SB(0, 1), cB + hsB, voffB); PG8_STAGE(PG8_SA(0, 0), cA, voffA); PG8_STAGE(PG8_SA(0, 1), cA + hsA, voffA);
;         if (wr == 1) PG8_BAR;
;         PG8_WAIT_V(2); PG8_BAR;
;         PG8_STAGE(PG8_SB(1, 0), cB + kstep, voffB); PG8_STAGE(PG8_SA(1, 0), cA + kstep, voffA); PG8_STAGE(PG8_SB(1, 1), cB + hsB + kstep, voffB);
;         PG8_WAIT_V(6); PG8_BAR;
.LBB0_1208:
	s_add_u32 s31, s86, 0xa000
	v_lshrrev_b32_e32 v3, 1, v0
	s_addc_u32 s33, s87, 0
	v_and_b32_e32 v3, 24, v3
	s_lshl_b32 s6, s6, 5
	v_and_b32_e32 v2, 15, v0
	v_lshlrev_b32_e32 v4, 1, v3
	v_lshlrev_b32_e32 v0, 2, v0
	s_and_b32 s8, s6, 0x60
	v_lshl_or_b32 v184, s7, 6, v2
	v_lshl_or_b32 v2, v2, 6, v4
	s_lshl_b32 s7, s7, 13
	v_and_b32_e32 v0, 32, v0
	s_lshl_b32 s6, s8, 7
	s_add_i32 s34, s21, 0x18000
	v_bitop3_b32 v5, v2, s6, v0 bitop3:0xde
	s_add_u32 s6, s12, 0x80
	v_bitop3_b32 v4, v2, s7, v0 bitop3:0xde
	s_waitcnt vmcnt(2)
	s_barrier
	s_addc_u32 s7, s13, 0
	s_mov_b32 m0, s34
	s_nop 0
	global_load_lds_dwordx4 v175, s[6:7]
	s_add_i32 s35, s21, 0x1a000
	s_add_i32 s36, s21, 0x8000
	s_mov_b32 m0, s35
	s_nop 0
	global_load_lds_dwordx4 v177, s[6:7]
	s_add_u32 s6, s14, 0x80
	s_addc_u32 s7, s15, 0
	s_mov_b32 m0, s36
	s_nop 0
	global_load_lds_dwordx4 v174, s[6:7]
	s_add_i32 s37, s21, 0xa000
	s_add_i32 s40, s21, 0x1c000
	s_mov_b32 m0, s37
	s_nop 0
	global_load_lds_dwordx4 v176, s[6:7]
	s_add_u32 s6, s12, 0x160080
	s_addc_u32 s7, s13, 0
	s_mov_b32 m0, s40
	s_nop 0
	global_load_lds_dwordx4 v175, s[6:7]
	s_add_i32 s41, s21, 0x1e000
	s_mov_b32 m0, s41
	s_nop 0
	global_load_lds_dwordx4 v177, s[6:7]
	v_readlane_b32 s6, v255, 8
	s_waitcnt vmcnt(6)
	v_or_b32_e32 v185, s8, v3
	v_mov_b32_e32 v2, v1
	v_mov_b32_e32 v3, v1
	v_readlane_b32 s7, v255, 9
	v_mov_b32_e32 v0, v1
	v_add_u32_e32 v186, 0, v5
	v_add_u32_e32 v187, 0, v4
	v_mov_b64_e32 v[6:7], v[2:3]
	v_mov_b64_e32 v[10:11], v[2:3]
	v_mov_b64_e32 v[22:23], v[2:3]
	v_mov_b64_e32 v[26:27], v[2:3]
	v_mov_b64_e32 v[38:39], v[2:3]
	v_mov_b64_e32 v[42:43], v[2:3]
	v_mov_b64_e32 v[54:55], v[2:3]
	v_mov_b64_e32 v[58:59], v[2:3]
	v_mov_b64_e32 v[14:15], v[2:3]
	v_mov_b64_e32 v[18:19], v[2:3]
	v_mov_b64_e32 v[30:31], v[2:3]
	v_mov_b64_e32 v[34:35], v[2:3]
	v_mov_b64_e32 v[46:47], v[2:3]
	v_mov_b64_e32 v[50:51], v[2:3]
	v_mov_b64_e32 v[62:63], v[2:3]
	v_mov_b64_e32 v[66:67], v[2:3]
	v_mov_b64_e32 v[70:71], v[2:3]
	v_mov_b64_e32 v[74:75], v[2:3]
	v_mov_b64_e32 v[86:87], v[2:3]
	v_mov_b64_e32 v[90:91], v[2:3]
	v_mov_b64_e32 v[102:103], v[2:3]
	v_mov_b64_e32 v[106:107], v[2:3]
	v_mov_b64_e32 v[130:131], v[2:3]
	v_mov_b64_e32 v[138:139], v[2:3]
	v_mov_b64_e32 v[78:79], v[2:3]
	v_mov_b64_e32 v[82:83], v[2:3]
	v_mov_b64_e32 v[94:95], v[2:3]
	v_mov_b64_e32 v[98:99], v[2:3]
	v_mov_b64_e32 v[110:111], v[2:3]
	v_mov_b64_e32 v[118:119], v[2:3]
	v_mov_b64_e32 v[142:143], v[2:3]
	v_mov_b64_e32 v[146:147], v[2:3]
	s_mov_b32 s49, s6
	v_readlane_b32 s6, v255, 4
	s_add_i32 s44, s21, 0xc000
	s_add_i32 s45, s21, 0xe000
	s_mov_b32 s16, 0
	v_mov_b64_e32 v[4:5], v[0:1]
	v_mov_b64_e32 v[8:9], v[0:1]
	v_mov_b64_e32 v[20:21], v[0:1]
	v_mov_b64_e32 v[24:25], v[0:1]
	v_mov_b64_e32 v[36:37], v[0:1]
	v_mov_b64_e32 v[40:41], v[0:1]
	v_mov_b64_e32 v[52:53], v[0:1]
	v_mov_b64_e32 v[56:57], v[0:1]
	v_mov_b64_e32 v[12:13], v[0:1]
	v_mov_b64_e32 v[16:17], v[0:1]
	v_mov_b64_e32 v[28:29], v[0:1]
	v_mov_b64_e32 v[32:33], v[0:1]
	v_mov_b64_e32 v[44:45], v[0:1]
	v_mov_b64_e32 v[48:49], v[0:1]
	v_mov_b64_e32 v[60:61], v[0:1]
	v_mov_b64_e32 v[64:65], v[0:1]
	v_mov_b64_e32 v[68:69], v[0:1]
	v_mov_b64_e32 v[72:73], v[0:1]
	v_mov_b64_e32 v[84:85], v[0:1]
	v_mov_b64_e32 v[88:89], v[0:1]
	v_mov_b64_e32 v[100:101], v[0:1]
	v_mov_b64_e32 v[104:105], v[0:1]
	v_mov_b64_e32 v[128:129], v[0:1]
	v_mov_b64_e32 v[136:137], v[0:1]
	v_mov_b64_e32 v[76:77], v[0:1]
	v_mov_b64_e32 v[80:81], v[0:1]
	v_mov_b64_e32 v[92:93], v[0:1]
	v_mov_b64_e32 v[96:97], v[0:1]
	v_mov_b64_e32 v[108:109], v[0:1]
	v_mov_b64_e32 v[116:117], v[0:1]
	v_mov_b64_e32 v[140:141], v[0:1]
	v_mov_b64_e32 v[144:145], v[0:1]
	s_mov_b32 s51, s6
	s_barrier
	v_readlane_b32 s7, v255, 5
	s_getreg_b32 s100, hwreg(HW_REG_HW_ID, 0, 6)
	s_lshl_b32 s100, s100, 2
	s_add_i32 s100, s100, 0x20540
	v_mov_b32_e32 v251, s100
	ds_read_b32 v251, v251
	s_waitcnt lgkmcnt(0)
	v_readfirstlane_b32 s100, v251
	s_cmp_ge_u32 s100, 4
	s_cbranch_scc1 statprio_skip5
	s_setprio 1

; __device__ __forceinline__ int mk_tid() { return mk_wave() * 64 + mk_lane(); }
;     __host__ __device__ bool next(int i, Unit& u) const { return StaticOrder::next(i >> 1, u); }
; template <class Epi, class Sched, bool ALIGN_EPI = false, bool SP2 = false>
; __device__ __forceinline__ void gemm_phase(PG8_LAS unsigned char* lds, const Gemm g, const Sched& S, const Epi& E) {
;     int tid_ = mk_tid(); asm volatile("" : "+v"(tid_));
;     const int tid = tid_, wid = __builtin_amdgcn_readfirstlane(tid >> 6), lane = tid & 63, wr = wid >> 2, wc = wid & 3, fr = lane & 15, fq = lane >> 4;
;     const int K = g.K, nt = K / BK;
;     unsigned voffA[2], voffB[2];
; #pragma unroll
;     for (int i = 0; i < 2; ++i) { int R, C; stage_rc(tid * 16 + i * 8192, R, C); const int Rb = Epi::PERM ? ((R & ~31) + perm32(R & 31)) : R;
;         voffA[i] = (unsigned)(R * g.lda + C) * 2u; voffB[i] = (unsigned)(Rb * g.ldb + C) * 2u; }
;     const size_t kstep = (size_t)(BK * 2);
;     const size_t hsA = (size_t)HALF * g.lda * 2, hsB = (size_t)HALF * g.ldb * 2;
;     const size_t tsA = 2 * hsA, tsB = 2 * hsB;
;     const unsigned ldsbase = (unsigned)(unsigned long long)lds;
;     const unsigned ldsw = (unsigned)wid * 1024u;
;     const int aoff = lds_byte(wr * 64 + fr, fq * 8), boff = lds_byte(wc * 32 + fr, fq * 8);
;     ...
;     Unit cur, nxt; int ui = 0; bool epi_ran = false;
;     if (!S.next(0, cur)) return;
;     f32x4 acc[2][2][4][2];
; #pragma unroll
;     for (int a = 0; a < 2; ++a)
; #pragma unroll
;         for (int b = 0; b < 2; ++b)
; #pragma unroll
;             for (int m = 0; m < 4; ++m)
; #pragma unroll
;                 for (int n = 0; n < 2; ++n) acc[a][b][m][n] = (f32x4){0.f, 0.f, 0.f, 0.f};
;     bf16x8 At[4][2], B0[2][2], B1[2][2];
;     const char* cA = (const char*)g.A + (size_t)cur.pm * tsA + (size_t)cur.k0 * 2; const char* cB = (const char*)g.Bt + (size_t)cur.pn * tsB + (size_t)cur.k0 * 2;
;     S.a_ready(cur);
;     if constexpr (SP2) {
;         PG8_STAGE(PG8_SB(0, 0), cB, voffB); PG8_STAGE(PG8_SB(0, 1), cB + hsB, voffB); PG8_STAGE(PG8_SA(0, 0), cA, voffA); PG8_STAGE(PG8_SA(0, 1), cA + hsA, voffA);
;         if (wr == 1) PG8_BAR;
;         PG8_WAIT_V(2); PG8_BAR;
;         PG8_STAGE(PG8_SB(1, 0), cB + kstep, voffB); PG8_STAGE(PG8_SA(1, 0), cA + kstep, voffA); PG8_STAGE(PG8_SB(1, 1), cB + hsB + kstep, voffB);
;         PG8_WAIT_V(6); PG8_BAR;
.LBB0_1236:
	v_bfe_u32 v2, v0, 4, 2
	s_add_u32 s35, s72, 0x58400000
	v_and_b32_e32 v3, 15, v0
	v_lshlrev_b32_e32 v5, 4, v2
	v_lshlrev_b32_e32 v0, 2, v0
	s_addc_u32 s36, s73, 0
	v_lshl_or_b32 v4, s7, 6, v3
	v_lshl_or_b32 v3, v3, 6, v5
	s_lshl_b32 s7, s7, 13
	v_and_b32_e32 v0, 32, v0
	v_bitop3_b32 v5, v3, s7, v0 bitop3:0xde
	s_lshl_b32 s7, s8, 5
	s_and_b32 s7, s7, 0x60
	s_lshl_b32 s8, s7, 7
	s_add_i32 s37, s26, 0x18000
	v_bitop3_b32 v3, v3, s8, v0 bitop3:0xde
	s_add_u32 s8, s16, 0x80
	s_waitcnt vmcnt(2)
	s_barrier
	s_addc_u32 s9, s17, 0
	s_mov_b32 m0, s37
	s_nop 0
	global_load_lds_dwordx4 v130, s[8:9]
	s_add_i32 s40, s26, 0x1a000
	s_add_i32 s41, s26, 0x8000
	s_mov_b32 m0, s40
	s_nop 0
	global_load_lds_dwordx4 v131, s[8:9]
	s_add_u32 s8, s18, 0x80
	s_addc_u32 s9, s19, 0
	s_mov_b32 m0, s41
	s_nop 0
	global_load_lds_dwordx4 v130, s[8:9]
	s_add_i32 s44, s26, 0xa000
	s_add_i32 s45, s26, 0x1c000
	s_mov_b32 m0, s44
	s_nop 0
	global_load_lds_dwordx4 v131, s[8:9]
	s_add_u32 s8, s16, 0x160080
	s_addc_u32 s9, s17, 0
	s_mov_b32 m0, s45
	s_nop 0
	global_load_lds_dwordx4 v130, s[8:9]
	s_add_i32 s46, s26, 0x1e000
	s_mov_b32 m0, s46
	s_nop 0
	global_load_lds_dwordx4 v131, s[8:9]
	s_add_i32 s47, s26, 0xc000
	s_waitcnt vmcnt(6)
	s_cmpk_lt_u32 s6, 0x100
	v_mov_b32_e32 v82, v1
	v_mov_b32_e32 v83, v1
	v_mov_b32_e32 v84, v1
	v_mov_b32_e32 v85, v1
	s_cselect_b64 s[8:9], -1, 0
	v_lshlrev_b32_e32 v0, 2, v2
	v_add_u32_e32 v132, 0xffffc000, v4
	s_lshl_b32 s84, s7, 2
	v_add_u32_e32 v133, 0, v3
	v_add_u32_e32 v134, 0, v5
	v_mov_b64_e32 v[96:97], v[84:85]
	v_mov_b64_e32 v[112:113], v[84:85]
	v_mov_b64_e32 v[108:109], v[84:85]
	v_mov_b64_e32 v[120:121], v[84:85]
	v_mov_b64_e32 v[116:117], v[84:85]
	v_mov_b64_e32 v[128:129], v[84:85]
	v_mov_b64_e32 v[124:125], v[84:85]
	v_mov_b64_e32 v[70:71], v[82:83]
	v_mov_b64_e32 v[66:67], v[82:83]
	v_mov_b64_e32 v[78:79], v[82:83]
	v_mov_b64_e32 v[74:75], v[82:83]
	v_mov_b64_e32 v[92:93], v[84:85]
	v_mov_b64_e32 v[88:89], v[84:85]
	v_mov_b64_e32 v[104:105], v[84:85]
	v_mov_b64_e32 v[100:101], v[84:85]
	v_mov_b64_e32 v[38:39], v[82:83]
	v_mov_b64_e32 v[34:35], v[82:83]
	v_mov_b64_e32 v[46:47], v[82:83]
	v_mov_b64_e32 v[42:43], v[82:83]
	v_mov_b64_e32 v[54:55], v[82:83]
	v_mov_b64_e32 v[50:51], v[82:83]
	v_mov_b64_e32 v[62:63], v[82:83]
	v_mov_b64_e32 v[58:59], v[82:83]
	v_mov_b64_e32 v[6:7], v[82:83]
	v_mov_b64_e32 v[2:3], v[82:83]
	v_mov_b64_e32 v[14:15], v[82:83]
	v_mov_b64_e32 v[10:11], v[82:83]
	v_mov_b64_e32 v[22:23], v[82:83]
	v_mov_b64_e32 v[18:19], v[82:83]
	v_mov_b64_e32 v[30:31], v[82:83]
	v_mov_b64_e32 v[26:27], v[82:83]
	v_readlane_b32 s6, v254, 33
	s_add_i32 s48, s26, 0xe000
	s_mov_b32 s20, 0
	v_lshlrev_b32_e32 v0, 2, v0
	v_mov_b64_e32 v[94:95], v[82:83]
	v_mov_b64_e32 v[110:111], v[82:83]
	v_mov_b64_e32 v[106:107], v[82:83]
	v_mov_b64_e32 v[118:119], v[82:83]
	v_mov_b64_e32 v[114:115], v[82:83]
	v_mov_b64_e32 v[126:127], v[82:83]
	v_mov_b64_e32 v[122:123], v[82:83]
	v_mov_b64_e32 v[72:73], v[84:85]
	v_mov_b64_e32 v[68:69], v[84:85]
	v_mov_b64_e32 v[80:81], v[84:85]
	v_mov_b64_e32 v[76:77], v[84:85]
	v_mov_b64_e32 v[90:91], v[82:83]
	v_mov_b64_e32 v[86:87], v[82:83]
	v_mov_b64_e32 v[102:103], v[82:83]
	v_mov_b64_e32 v[98:99], v[82:83]
	v_mov_b64_e32 v[40:41], v[84:85]
	v_mov_b64_e32 v[36:37], v[84:85]
	v_mov_b64_e32 v[48:49], v[84:85]
	v_mov_b64_e32 v[44:45], v[84:85]
	v_mov_b64_e32 v[56:57], v[84:85]
	v_mov_b64_e32 v[52:53], v[84:85]
	v_mov_b64_e32 v[64:65], v[84:85]
	v_mov_b64_e32 v[60:61], v[84:85]
	v_mov_b64_e32 v[8:9], v[84:85]
	v_mov_b64_e32 v[4:5], v[84:85]
	v_mov_b64_e32 v[16:17], v[84:85]
	v_mov_b64_e32 v[12:13], v[84:85]
	v_mov_b64_e32 v[24:25], v[84:85]
	v_mov_b64_e32 v[20:21], v[84:85]
	v_mov_b64_e32 v[32:33], v[84:85]
	v_mov_b64_e32 v[28:29], v[84:85]
	v_readlane_b32 s63, v254, 45
	s_mov_b32 s53, s6
	v_readlane_b32 s57, v254, 29
	s_barrier
	v_readlane_b32 s7, v254, 34
	s_getreg_b32 s100, hwreg(HW_REG_HW_ID, 0, 6)
	s_lshl_b32 s100, s100, 2
	s_add_i32 s100, s100, 0x20540
	v_mov_b32_e32 v251, s100
	ds_read_b32 v251, v251
	s_waitcnt lgkmcnt(0)
	v_readfirstlane_b32 s100, v251
	s_cmp_ge_u32 s100, 4
	s_cbranch_scc1 statprio_skip6
	s_setprio 1
